# v17 + forgetting attention: next work-unit id fetched one unit ahead (counter atomic issued in the unit prologue, consumed at the next loop head)
# baseline (speedup 1.0000x reference)
; #define LAS __attribute__((address_space(3)))
; #define WSP(T, off) ((T*)wsoff(off))
; template <int MODE> ...
;     LAS int* slot = (LAS int*)(lds + 147456 - 128);
;     for (;;) {
;         int idx;
;         if (counter) {
;             if (threadIdx.x == 0) *slot = (int)__hip_atomic_fetch_add(counter, 1u, __ATOMIC_RELAXED, __HIP_MEMORY_SCOPE_AGENT);
;             __syncthreads(); idx = *slot - idx0; __syncthreads();
; __global__ void __launch_bounds__(512, 2) fwd_kernel(Args args) {
;     ...
;             attn_units<att::M_FOX>(lds, WSP(unsigned, WS_CNT) + 64, 0, 1024, 16, 0, true, WSP(bf16_t, WS_Q), 1024, WSP(bf16_t, WS_K), WSP(bf16_t, WS_V), 1024, WSP(bf16_t, WS_O), 1024, WSP(float, WS_CF), WSP(unsigned, WS_KMX), nullptr);
.LBB0_942:
	s_or_b64 exec, exec, s[4:5]
	s_mov_b64 s[0:1], 0xa8
	s_waitcnt lgkmcnt(0)
	s_barrier
	s_add_u32 s0, s74, s0
	s_addc_u32 s1, s75, s1
	s_load_dwordx2 s[0:1], s[0:1], 0x0
	s_mov_b64 s[2:3], 0x101000
	s_waitcnt lgkmcnt(0)
	s_add_u32 s12, s0, s2
	s_addc_u32 s13, s1, s3
	s_mov_b64 s[0:1], 0xa8
	s_add_u32 s0, s74, s0
	s_addc_u32 s1, s75, s1
	s_load_dwordx2 s[0:1], s[0:1], 0x0
	s_mov_b64 s[2:3], 0x7200000
	s_waitcnt lgkmcnt(0)
	s_add_u32 s30, s0, s2
	s_addc_u32 s31, s1, s3
	s_mov_b64 s[0:1], 0xa8
	s_add_u32 s0, s74, s0
	s_addc_u32 s1, s75, s1
	s_load_dwordx2 s[0:1], s[0:1], 0x0
	s_mov_b64 s[2:3], 0x9200000
	s_waitcnt lgkmcnt(0)
	s_add_u32 s14, s0, s2
	s_addc_u32 s15, s1, s3
	s_mov_b64 s[0:1], 0xa8
	s_add_u32 s0, s74, s0
	s_addc_u32 s1, s75, s1
	s_load_dwordx2 s[0:1], s[0:1], 0x0
	s_mov_b64 s[2:3], 0xb200000
	s_waitcnt lgkmcnt(0)
	s_add_u32 s16, s0, s2
	s_addc_u32 s17, s1, s3
	s_mov_b64 s[0:1], 0xa8
	s_add_u32 s0, s74, s0
	s_addc_u32 s1, s75, s1
	s_load_dwordx2 s[0:1], s[0:1], 0x0
	s_mov_b64 s[2:3], 0xd200000
	s_waitcnt lgkmcnt(0)
	s_add_u32 s34, s0, s2
	s_addc_u32 s35, s1, s3
	s_mov_b64 s[0:1], 0xa8
	s_add_u32 s0, s74, s0
	s_addc_u32 s1, s75, s1
	s_load_dwordx2 s[0:1], s[0:1], 0x0
	s_mov_b64 s[2:3], 0x300000
	s_waitcnt lgkmcnt(0)
	s_add_u32 s36, s0, s2
	s_addc_u32 s37, s1, s3
	s_mov_b64 s[0:1], 0xa8
	s_add_u32 s0, s74, s0
	s_addc_u32 s1, s75, s1
	s_load_dwordx2 s[0:1], s[0:1], 0x0
	s_mov_b64 s[2:3], 0x100000
	s_waitcnt lgkmcnt(0)
	s_add_u32 s38, s0, s2
	s_addc_u32 s39, s1, s3
	s_cmp_lg_u64 s[0:1], 0
	s_cselect_b64 s[18:19], -1, 0
	s_add_u32 s40, s36, 0xffffff00
	s_addc_u32 s41, s37, -1
	s_mov_b32 s101, 0
	s_branch .LBB0_946

; template <int MODE> ...
;     ...
;         int idx;
;         if (counter) {
;             if (threadIdx.x == 0) *slot = (int)__hip_atomic_fetch_add(counter, 1u, __ATOMIC_RELAXED, __HIP_MEMORY_SCOPE_AGENT);
;             __syncthreads(); idx = *slot - idx0; __syncthreads();
;             if (idx >= nunits) break;
;             if (idx < 0) continue;
;         } else { idx = (int)blockIdx.x; if (idx >= nunits) break; }
;         const int h = head_major ? (nheads - 1 - idx / 64) : (idx % nheads), qb = head_major ? (63 - idx % 64) : (63 - idx / nheads), hh = head0 + h;
;         att::AttnArgs a; a.Q = Q + hh * 64; a.ldq = ldq; a.K = K + hh * 64; a.V = V + hh * 64; a.ldkv = ldkv; a.O = O + hh * 64; a.ldo = ldo;
;         a.cf = cf ? cf + (size_t)hh * S : nullptr; a.kmax2 = kmx ? (__uint_as_float(kmx[2 * hh]) + __uint_as_float(kmx[2 * hh + 1])) * 1.02f : 0.f;
.LBB0_946:
	s_and_saveexec_b64 s[4:5], s[58:59]
	s_cbranch_execz .LBB0_950
	s_cmp_lg_u32 s101, 0
	s_cbranch_scc1 .LBB0_949
	v_mov_b32_e32 v228, 1
	global_atomic_add v228, v1, v228, s[12:13] offset:256 sc0
.LBB0_949:
	s_waitcnt vmcnt(0)
	v_mov_b32_e32 v2, s95
	ds_write_b32 v2, v228
.LBB0_950:
	s_or_b64 exec, exec, s[4:5]
	s_mov_b32 s101, 0
	v_mov_b32_e32 v0, s95
	s_waitcnt lgkmcnt(0)
	s_barrier
	ds_read_b32 v0, v0
	s_movk_i32 s1, 0x3ff
	s_mov_b64 s[4:5], -1
	s_waitcnt lgkmcnt(0)
	s_barrier
	v_cmp_lt_i32_e32 vcc, s1, v0
	v_readfirstlane_b32 s0, v0
	s_cbranch_vccnz .LBB0_945
	s_cmp_lt_i32 s0, 0
	s_cbranch_scc1 .LBB0_944
	s_lshr_b32 s1, s0, 6
	s_sub_i32 s1, 15, s1
	v_mov_b32_e32 v157, 0
	s_andn2_b64 vcc, exec, s[18:19]
	v_mov_b32_e32 v9, 0
	s_cbranch_vccnz .LBB0_954
	s_lshl_b32 s80, s1, 1
	s_lshl_b64 s[2:3], s[80:81], 2
	s_add_u32 s2, s38, s2
	s_addc_u32 s3, s39, s3
	global_load_dwordx2 v[2:3], v1, s[2:3]
	s_waitcnt vmcnt(0)
	v_add_f32_e32 v0, v2, v3
	v_mul_f32_e32 v9, 0x3f828f5c, v0

; __device__ __forceinline__ float bf2f(short s) { return __uint_as_float(((unsigned)(unsigned short)s) << 16); }
; #define LOADT(i, kreg, vreg, creg) do { const int k0_ = KEY0(i); kreg = *(const u32x4*)(A.K + (size_t)(k0_ + lane) * A.ldkv + wid * 8); vreg = *(const u32x4*)(A.V + (size_t)(k0_ + lane) * A.ldkv + wid * 8); \
;         if (MODE == M_FOX) { if (tid < 64) creg = A.cf[k0_ + tid] * LOG2E; } } while (0)
; template <int MODE>
; __device__ __forceinline__ void attn_unit(LAS unsigned char* lds, const AttnArgs& A, int qb) {
;     ...
;     if (MODE == M_FOX) {
;         float s = 0.f;
; #pragma unroll
;         for (int d0 = 0; d0 < 4; ++d0)
; #pragma unroll
;             for (int e = 0; e < 8; ++e) { const float x = bf2f(qr[d0][e]); s += x * x; }
;         s += __shfl_xor(s, 32);
;         qb2 = sqrtf(s * A.kmax2) * C2 * 1.01f;
;         cq2 = A.cf[row] * LOG2E;
;     }
;     const int NT = (MODE == M_XA || MODE == M_MOBA) ? 4 : (q0 / 64 + 4);
;     f32x16 o0, o1;
; #pragma unroll
;     for (int r = 0; r < 16; ++r) { o0[r] = 0.f; o1[r] = 0.f; }
;     float m_run = -1e30f, l_run = 0.f, T = 0.f;
;     u32x4 k1 = (u32x4){0u, 0u, 0u, 0u}, v1 = k1, k2 = k1, v2 = k1, k3 = k1, v3 = k1; float c1 = 0.f, c2 = 0.f, c3 = 0.f;
;     ...
;     LOADT(0, k1, v1, c1); if (NT > 1) LOADT(1, k2, v2, c2); if (NT > 2) LOADT(2, k3, v3, c3);
;     STORET(0, k1, v1, c1);
;     __syncthreads();
; template <int MODE> ...
;     ...
;             if (threadIdx.x == 0) *slot = (int)__hip_atomic_fetch_add(counter, 1u, __ATOMIC_RELAXED, __HIP_MEMORY_SCOPE_AGENT);
.LBB0_960:
	s_or_b64 exec, exec, s[4:5]
	s_lshl_b32 s2, s42, 10
	s_add_i32 s46, s2, 0
	v_lshlrev_b32_e32 v179, 4, v6
	s_lshl_b32 s3, s42, 7
	v_add_u32_e32 v180, s46, v179
	s_add_i32 s46, s46, s3
	v_lshlrev_b32_e32 v181, 1, v6
	v_add_u32_e32 v182, s46, v181
	v_lshl_add_u32 v183, v2, 2, 0
	s_waitcnt vmcnt(5)
	ds_write_b128 v180, v[114:117]
	s_waitcnt vmcnt(4)
	ds_write_b16 v182, v118 offset:8192
	ds_write_b16_d16_hi v182, v118 offset:8336
	ds_write_b16 v182, v119 offset:8480
	ds_write_b16_d16_hi v182, v119 offset:8624
	ds_write_b16 v182, v120 offset:8768
	ds_write_b16_d16_hi v182, v120 offset:8912
	ds_write_b16 v182, v121 offset:9056
	ds_write_b16_d16_hi v182, v121 offset:9200
	s_and_saveexec_b64 s[4:5], s[6:7]
	ds_write_b32 v183, v157 offset:17408
	s_or_b64 exec, exec, s[4:5]
	s_waitcnt lgkmcnt(9)
	v_add_f32_e32 v4, v10, v12
	v_mul_f32_e32 v4, v9, v4
	s_mov_b32 s2, 0xf800000
	v_mul_f32_e32 v5, 0x4f800000, v4
	v_cmp_gt_f32_e32 vcc, s2, v4
	s_mul_i32 s4, s42, 0xfffffb84
	s_add_i32 s46, s46, s4
	v_cndmask_b32_e32 v4, v4, v5, vcc
	v_sqrt_f32_e32 v5, v4
	s_mov_b32 s4, 0x3fb8aa3b
	v_mul_f32_e32 v184, 0x3fb8aa3b, v11
	s_lshl_b32 s44, s0, 2
	v_add_u32_e32 v9, -1, v5
	v_fma_f32 v10, -v9, v5, v4
	v_cmp_ge_f32_e64 s[8:9], 0, v10
	v_add_u32_e32 v10, 1, v5
	s_add_i32 s45, s44, 4
	v_cndmask_b32_e64 v9, v5, v9, s[8:9]
	v_fma_f32 v5, -v10, v5, v4
	v_cmp_lt_f32_e64 s[8:9], 0, v5
	s_or_b32 s47, s44, 2
	s_or_b32 s48, s43, 31
	v_cndmask_b32_e64 v5, v9, v10, s[8:9]
	v_mul_f32_e32 v9, 0x37800000, v5
	v_cndmask_b32_e32 v5, v5, v9, vcc
	v_mov_b32_e32 v9, 0x260
	v_cmp_class_f32_e32 vcc, v4, v9
	s_add_i32 s52, s80, 0xff
	s_lshl_b32 s0, s0, 10
	v_cndmask_b32_e32 v4, v5, v4, vcc
	v_mul_f32_e32 v4, 0x3e38aa3b, v4
	v_mul_f32_e32 v5, 0x3f8147ae, v4
	v_min_f32_e32 v189, 0x42400000, v5
	v_fma_f32 v160, v11, s4, -v189
	s_mul_i32 s4, s42, 0x3fc
	s_add_i32 s49, s46, s4
	s_add_i32 s50, s49, s3
	s_sub_i32 s3, s80, 64
	v_fmamk_f32 v190, v4, 0x3f8147ae, v184
	v_add_u32_e32 v4, s3, v6
	v_ashrrev_i32_e32 v5, 31, v4
	v_lshlrev_b64 v[4:5], 11, v[4:5]
	v_lshl_add_u64 v[4:5], v[4:5], 0, s[10:11]
	s_add_i32 s3, s80, 0xffffff80
	v_lshl_add_u64 v[162:163], s[14:15], 0, v[4:5]
	v_lshl_add_u64 v[164:165], s[16:17], 0, v[4:5]
	v_add_u32_e32 v4, s3, v6
	s_add_u32 s1, s40, s1
	v_lshlrev_b32_e32 v10, 1, v2
	v_lshrrev_b32_e32 v12, 1, v2
	v_ashrrev_i32_e32 v5, 31, v4
	s_addc_u32 s3, s41, 0
	v_lshlrev_b32_e32 v156, 3, v7
	v_and_b32_e32 v9, 19, v2
	v_and_b32_e32 v10, 8, v10
	v_and_b32_e32 v12, 4, v12
	v_lshlrev_b32_e32 v187, 10, v7
	v_cmp_eq_u32_e64 s[8:9], 0, v6
	v_lshlrev_b64 v[4:5], 11, v[4:5]
	v_add_lshl_u32 v6, s80, v6, 11
	v_mov_b32_e32 v7, v1
	s_add_u32 s0, s1, s0
	v_mov_b32_e32 v80, v1
	v_mov_b32_e32 v81, v1
	v_mov_b32_e32 v140, v1
	v_mov_b32_e32 v141, v1
	v_or3_b32 v9, v10, v9, v12
	v_mul_u32_u24_e32 v185, 0x90, v8
	v_lshl_add_u64 v[4:5], v[4:5], 0, s[10:11]
	v_lshl_add_u64 v[6:7], v[6:7], 0, s[10:11]
	s_addc_u32 s1, s3, 0
	v_mov_b32_e32 v66, v1
	v_mov_b32_e32 v67, v1
	v_mov_b32_e32 v68, v1
	v_mov_b32_e32 v69, v1
	v_mov_b32_e32 v70, v1
	v_mov_b32_e32 v71, v1
	v_mov_b32_e32 v72, v1
	v_mov_b32_e32 v73, v1
	v_mov_b32_e32 v74, v1
	v_mov_b32_e32 v75, v1
	v_mov_b32_e32 v76, v1
	v_mov_b32_e32 v77, v1
	v_mov_b32_e32 v78, v1
	v_mov_b32_e32 v79, v1
	v_mov_b32_e32 v138, v1
	v_mov_b32_e32 v139, v1
	v_mov_b64_e32 v[148:149], v[140:141]
	v_mov_b64_e32 v[144:145], v[140:141]
	v_mov_b64_e32 v[152:153], v[140:141]
	v_mov_b64_e32 v[96:97], v[80:81]
	v_lshlrev_b64 v[158:159], 10, v[154:155]
	s_mov_b32 s2, 0
	s_mov_b32 s51, 8
	v_lshl_add_u32 v186, v9, 4, 0
	v_lshl_add_u32 v188, v156, 2, 0
	v_mov_b32_e32 v161, v160
	v_add3_u32 v191, 0, v185, v0
	v_lshl_add_u64 v[166:167], s[16:17], 0, v[4:5]
	v_lshl_add_u64 v[168:169], s[14:15], 0, v[6:7]
	v_lshl_add_u64 v[170:171], s[16:17], 0, v[6:7]
	v_lshl_add_u64 v[172:173], v[2:3], 2, s[0:1]
	v_lshl_add_u64 v[174:175], s[14:15], 0, v[4:5]
	v_mov_b32_e32 v193, 0xf149f2ca
	v_mov_b32_e32 v155, 0
	s_mov_b64 s[4:5], 0
	s_mov_b32 s53, 5
	v_mov_b64_e32 v[146:147], v[138:139]
	v_mov_b64_e32 v[142:143], v[138:139]
	v_mov_b64_e32 v[150:151], v[138:139]
	v_mov_b64_e32 v[94:95], v[78:79]
	v_mov_b64_e32 v[92:93], v[76:77]
	v_mov_b64_e32 v[90:91], v[74:75]
	v_mov_b64_e32 v[88:89], v[72:73]
	v_mov_b64_e32 v[86:87], v[70:71]
	v_mov_b64_e32 v[84:85], v[68:69]
	v_mov_b64_e32 v[82:83], v[66:67]
	v_mov_b64_e32 v[2:3], v[66:67]
	v_mov_b64_e32 v[4:5], v[66:67]
	v_mov_b64_e32 v[6:7], v[66:67]
	v_mov_b64_e32 v[8:9], v[66:67]
	v_mov_b64_e32 v[10:11], v[66:67]
	v_mov_b64_e32 v[12:13], v[66:67]
	v_mov_b64_e32 v[14:15], v[66:67]
	v_mov_b64_e32 v[16:17], v[66:67]
	v_mov_b64_e32 v[18:19], v[66:67]
	v_mov_b64_e32 v[20:21], v[66:67]
	v_mov_b64_e32 v[22:23], v[66:67]
	v_mov_b64_e32 v[24:25], v[66:67]
	v_mov_b64_e32 v[26:27], v[66:67]
	v_mov_b64_e32 v[28:29], v[66:67]
	v_mov_b64_e32 v[30:31], v[66:67]
	v_mov_b64_e32 v[32:33], v[66:67]
	s_and_saveexec_b64 s[10:11], s[58:59]
	v_mov_b32_e32 v228, 1
	global_atomic_add v228, v1, v228, s[12:13] offset:256 sc0
	s_mov_b64 exec, s[10:11]
	s_mov_b32 s101, 1
	s_waitcnt lgkmcnt(0)
	s_barrier
	s_branch .LBB0_964
